# dataflow seam 3: mid-P3 QKV/AUG arrival after 2nd unit, P6 starts without chip-wide rendezvous; P8 waits for P3-done word
# baseline (speedup 1.0000x reference)
; #define PG8_BAR __builtin_amdgcn_s_barrier()
; template <class Epi, bool ALIGN_EPI>
; __device__ __forceinline__ void gemm_phase(LAS unsigned char* lds, const Gemm g, const StaticOrder& S, const Epi& E) {
;     ...
;         if constexpr (ALIGN_EPI) { if (wr == 0) PG8_BAR; }
;         E(acc, cur, wr, wc, fr, fq);
;         if (!has_next) break;
; #pragma unroll
;         for (int a = 0; a < 2; ++a)
; #pragma unroll
;             for (int b = 0; b < 2; ++b)
; #pragma unroll
;                 for (int m = 0; m < 4; ++m)
; #pragma unroll
;                     for (int n = 0; n < 2; ++n) acc[a][b][m][n] = (f32x4){0.f, 0.f, 0.f, 0.f};
;         cur = nxt; cA = nA; cB = nB; ++ui;
;         if constexpr (ALIGN_EPI) { if (wr == 1) PG8_BAR; }
;     }
; __global__ void __launch_bounds__(NWAVES * 64, 2) mega_fwd(Args args) {
;     ...
;     if (IN(3)) { pg8::Gemm g{XB, Win, M, NIN, DM, DM, DM, 0, 0, 1}; pg8::StaticOrder S; S.init(M, NIN, 1, G, bx);
;         pg8::EpiInProj E{ss1, QB_, KB, VB, AUG, (unsigned char*)GATES, args.in[8], args.in[9]}; pg8::gemm_phase<pg8::EpiInProj, true>(lds, g, S, E);
.LBB0_514:
	s_cmp_eq_u32 s35, 2
	s_cbranch_scc0 .Lqkv_skip
	s_waitcnt vmcnt(0)
	s_barrier
	v_cmp_eq_u32_e32 vcc, 0, v0
	s_and_saveexec_b64 s[100:101], vcc
	s_cbranch_execz .Lqkv_join
	buffer_wbl2 sc1
	s_waitcnt vmcnt(0)
	v_mov_b32_e32 v130, 0xfd0f400
	v_mov_b32_e32 v131, 1
	global_atomic_add v130, v131, s[66:67]
.Lqkv_join:
	s_or_b64 exec, exec, s[100:101]
.Lqkv_skip:
	s_andn2_b64 vcc, exec, s[4:5]
	s_mov_b64 s[4:5], -1
	s_cbranch_vccnz .LBB0_415
	s_andn2_b64 vcc, exec, s[84:85]
	s_cbranch_vccnz .LBB0_414
	s_barrier
	s_branch .LBB0_414

; __device__ __forceinline__ unsigned xb_ld(unsigned* p)              { return __hip_atomic_load(p, __ATOMIC_RELAXED, __HIP_MEMORY_SCOPE_AGENT); }
; __device__ __forceinline__ unsigned xb_add(unsigned* p, unsigned v) { return __hip_atomic_fetch_add(p, v, __ATOMIC_RELAXED, __HIP_MEMORY_SCOPE_AGENT); }
; #define XB_SPIN(cond, bar) do { unsigned _sp = 0; while (cond) { __builtin_amdgcn_s_sleep(1); \
;     if ((++_sp & 255u) == 0u) { if (xb_ld(&(bar)[XB_TMO])) break; if (_sp > XB_SPIN_CAP) { atomicAdd(&(bar)[XB_TMO], 1u); break; } } } } while (0)
; #define SEAM(k) do { if (IN(k) && IN((k) + 1)) xcd_barrier(bar); } while (0)
; __device__ __forceinline__ void xcd_barrier(const XcdBarrier& b) {
;     asm volatile("s_waitcnt vmcnt(0)" ::: "memory");
;     __syncthreads();
;     if (threadIdx.x == 0) {
;         unsigned* bar = b.bar;
;         __builtin_amdgcn_s_waitcnt(0);
;         unsigned nloc = b.st[0], nx = b.st[1];
;         if (nloc == 0u) { xcd_barrier_complete(bar, b.x, nloc, nx); b.st[0] = nloc; b.st[1] = nx; }
;         const unsigned old = xb_add(&bar[XB_XSUB(b.x)], 1u);
;         const unsigned gen = old / nloc;
;         if (old + 1u == (gen + 1u) * nloc) {
;             __builtin_amdgcn_fence(__ATOMIC_RELEASE, "agent");
;             asm volatile("s_waitcnt vmcnt(0)" ::: "memory");
;             const unsigned og = xb_add(&bar[XB_TOP], 1u);
;             const unsigned tg = og / nx;
;             if (og + 1u == (tg + 1u) * nx) xb_add(&bar[XB_TOPGEN], 1u);
;             else XB_SPIN(xb_ld(&bar[XB_TOPGEN]) == tg, bar);
;             __builtin_amdgcn_fence(__ATOMIC_ACQUIRE, "agent");
;             xb_add(&bar[XB_XGEN(b.x)], 1u);
;             asm volatile("s_waitcnt vmcnt(0)" ::: "memory");
;         } else {
;             XB_SPIN(xb_ld(&bar[XB_XGEN(b.x)]) == gen, bar);
;             __builtin_amdgcn_fence(__ATOMIC_ACQUIRE, "agent");
;             asm volatile("s_waitcnt vmcnt(0)" ::: "memory");
;         }
;     }
;     __syncthreads();
; }
; __global__ void __launch_bounds__(NWAVES * 64, 2) mega_fwd(Args args) {
;     ...
;     SEAM(3);
.LBB0_604:
	s_cmp_gt_u32 s85, 4
	s_cselect_b64 s[0:1], -1, 0
	v_writelane_b32 v252, s94, 8
	s_and_b64 s[0:1], s[26:27], s[0:1]
	v_readlane_b32 s74, v251, 18
	v_readlane_b32 s68, v251, 20
	v_readlane_b32 s80, v251, 56
	v_writelane_b32 v252, s95, 9
	s_andn2_b64 vcc, exec, s[0:1]
	v_readlane_b32 s75, v251, 19
	v_readlane_b32 s69, v251, 21
	v_readlane_b32 s81, v251, 57
	s_cbranch_vccnz .LBB0_658
	s_waitcnt vmcnt(0)
	s_waitcnt vmcnt(0) lgkmcnt(0)
	s_barrier
	s_and_saveexec_b64 s[0:1], s[74:75]
	s_cbranch_execz .LBB0_657
	buffer_inv sc1
	buffer_wbl2 sc1
	s_waitcnt vmcnt(0)
	v_mov_b32_e32 v2, 1
	v_mov_b32_e32 v1, 0xfd0fc00
	global_atomic_add v1, v2, s[66:67]
	s_sub_i32 s2, s88, 64
	s_cmpk_lt_u32 s2, 0x80
	s_cbranch_scc0 .Ldf3_nos5
	v_mov_b32_e32 v1, 0xfd0f800
	global_atomic_add v1, v2, s[66:67]
.Ldf3_nos5:
	v_mov_b32_e32 v1, 0xfd0f400
	v_mov_b32_e32 v3, 0xfd0f800
	s_mov_b32 s3, 0
.Ldf3_spin:
	global_load_dword v4, v1, s[66:67] sc1
	global_load_dword v5, v3, s[66:67] sc1
	s_waitcnt vmcnt(0)
	v_readfirstlane_b32 s4, v4
	v_readfirstlane_b32 s5, v5
	s_nop 3
	s_cmp_ge_u32 s4, 0x100
	s_cselect_b32 s4, 1, 0
	s_cmp_ge_u32 s5, 0x80
	s_cselect_b32 s5, 1, 0
	s_cmpk_gt_i32 s88, 63
	s_cselect_b32 s6, 1, 0
	s_or_b32 s5, s5, s6
	s_and_b32 s4, s4, s5
	s_cmp_lg_u32 s4, 0
	s_cbranch_scc1 .Ldf3_ok
	s_sleep 1
	s_add_i32 s3, s3, 1
	s_cmp_lt_u32 s3, 0x20000
	s_cbranch_scc1 .Ldf3_spin

; __device__ __forceinline__ unsigned xb_ld(unsigned* p)              { return __hip_atomic_load(p, __ATOMIC_RELAXED, __HIP_MEMORY_SCOPE_AGENT); }
; __device__ __forceinline__ unsigned xb_add(unsigned* p, unsigned v) { return __hip_atomic_fetch_add(p, v, __ATOMIC_RELAXED, __HIP_MEMORY_SCOPE_AGENT); }
; #define XB_SPIN(cond, bar) do { unsigned _sp = 0; while (cond) { __builtin_amdgcn_s_sleep(1); \
;     if ((++_sp & 255u) == 0u) { if (xb_ld(&(bar)[XB_TMO])) break; if (_sp > XB_SPIN_CAP) { atomicAdd(&(bar)[XB_TMO], 1u); break; } } } } while (0)
; #define SEAM(k) do { if (IN(k) && IN((k) + 1)) xcd_barrier(bar); } while (0)
; __device__ __forceinline__ void xcd_barrier(const XcdBarrier& b) {
;     asm volatile("s_waitcnt vmcnt(0)" ::: "memory");
;     __syncthreads();
;     if (threadIdx.x == 0) {
;         unsigned* bar = b.bar;
;         __builtin_amdgcn_s_waitcnt(0);
;         unsigned nloc = b.st[0], nx = b.st[1];
;         if (nloc == 0u) { xcd_barrier_complete(bar, b.x, nloc, nx); b.st[0] = nloc; b.st[1] = nx; }
;         const unsigned old = xb_add(&bar[XB_XSUB(b.x)], 1u);
;         const unsigned gen = old / nloc;
;         if (old + 1u == (gen + 1u) * nloc) {
;             __builtin_amdgcn_fence(__ATOMIC_RELEASE, "agent");
;             asm volatile("s_waitcnt vmcnt(0)" ::: "memory");
;             const unsigned og = xb_add(&bar[XB_TOP], 1u);
;             const unsigned tg = og / nx;
;             if (og + 1u == (tg + 1u) * nx) xb_add(&bar[XB_TOPGEN], 1u);
;             else XB_SPIN(xb_ld(&bar[XB_TOPGEN]) == tg, bar);
;             __builtin_amdgcn_fence(__ATOMIC_ACQUIRE, "agent");
;             xb_add(&bar[XB_XGEN(b.x)], 1u);
;             asm volatile("s_waitcnt vmcnt(0)" ::: "memory");
;         } else {
;             XB_SPIN(xb_ld(&bar[XB_XGEN(b.x)]) == gen, bar);
;             __builtin_amdgcn_fence(__ATOMIC_ACQUIRE, "agent");
;             asm volatile("s_waitcnt vmcnt(0)" ::: "memory");
;         }
;     }
;     __syncthreads();
; }
; __global__ void __launch_bounds__(NWAVES * 64, 2) mega_fwd(Args args) {
;     ...
;     SEAM(7);
.LBB0_1034:
	s_cmp_gt_i32 s85, 8
	s_cselect_b64 s[2:3], -1, 0
	s_and_b64 s[4:5], s[4:5], s[2:3]
	s_andn2_b64 vcc, exec, s[4:5]
	s_cbranch_vccnz .LBB0_1088
	s_waitcnt vmcnt(0)
	s_waitcnt vmcnt(0) lgkmcnt(0)
	s_barrier
	s_and_saveexec_b64 s[4:5], s[74:75]
	s_cbranch_execz .LBB0_1087
	buffer_inv sc1
	s_and_b32 s6, s88, 7
	s_lshl_b32 s6, s6, 3
	s_bfe_u32 s7, s88, 0x30003
	s_or_b32 s6, s6, s7
	s_lshl_b32 s6, s6, 6
	s_add_i32 s6, s6, 0xfd0d000
	v_mov_b32_e32 v1, s6
	v_mov_b32_e32 v2, 0xfd0ec00
	v_mov_b32_e32 v3, 0xfd08000
	s_mov_b32 s8, 0
	v_mov_b32_e32 v18, 0xfd0fc00
.Ldf7_spin:
	global_load_dword v4, v1, s[66:67] sc1
	global_load_dword v5, v1, s[66:67] offset:32 sc1
	global_load_dword v6, v2, s[66:67] sc1
	global_load_dword v16, v3, s[66:67] sc1
	global_load_dword v17, v18, s[66:67] sc1
	s_waitcnt vmcnt(0)
	v_readfirstlane_b32 s9, v4
	v_readfirstlane_b32 s10, v5
	v_readfirstlane_b32 s11, v6
	v_readfirstlane_b32 s12, v16
	v_readfirstlane_b32 s13, v17
	s_nop 3
	s_cmp_ge_u32 s9, 8
	s_cselect_b32 s9, 1, 0
	s_cmp_ge_u32 s10, 2
	s_cselect_b32 s10, 1, 0
	s_cmp_ge_u32 s11, 64
	s_cselect_b32 s11, 1, 0
	s_cmp_ge_u32 s12, 0xc0
	s_cselect_b32 s12, 1, 0
	s_cmp_ge_u32 s13, 0x100
	s_cselect_b32 s13, 1, 0
	s_and_b32 s9, s9, s13
	s_and_b32 s9, s9, s10
	s_and_b32 s11, s11, s12
	s_and_b32 s9, s9, s11
	s_cmp_lg_u32 s9, 0
	s_cbranch_scc1 .Ldf7_ok
	s_sleep 1
	s_add_i32 s8, s8, 1
	s_cmp_lt_u32 s8, 0x20000
	s_cbranch_scc1 .Ldf7_spin
